# P4 final tile: residual fragments fetched by the last BODY's free staging DMAs into the ring and read from LDS in the epilogue (as in fused P6)
# speedup vs baseline: 1.0113x; 1.0028x over previous
.LBB0_623:
	s_add_u32 s6, s20, 0x100
	s_addc_u32 s7, s21, 0
	s_cmp_eq_u32 s59, 20
	s_cselect_b32 s24, s10, s6
	s_cselect_b32 s25, s11, s7
	s_cselect_b32 s27, s13, s58
	s_cselect_b32 s26, s12, s55
	s_add_u32 s16, s24, 0x80
	s_addc_u32 s17, s25, 0
	s_add_u32 s18, s26, 0x80
	s_addc_u32 s19, s27, 0
	s_add_u32 s60, s20, 0x60080
	s_addc_u32 s61, s21, 0
	s_add_u32 s22, s24, 0x60000
	s_addc_u32 s23, s25, 0
	s_add_u32 s28, s26, 0x60000
	s_addc_u32 s29, s27, 0
	s_add_u32 s20, s26, 0x60080
	s_addc_u32 s21, s27, 0
	ds_read_b128 v[130:133], v187
	ds_read_b128 v[134:137], v187 offset:1024
	ds_read_b128 v[138:141], v187 offset:2048
	ds_read_b128 v[142:145], v187 offset:3072
	ds_read_b128 v[146:149], v189
	ds_read_b128 v[150:153], v189 offset:1024
	ds_read_b128 v[154:157], v189 offset:2048
	ds_read_b128 v[158:161], v189 offset:3072
	s_mov_b32 m0, s47
	ds_read_b128 v[162:165], v191
	ds_read_b128 v[166:169], v191 offset:1024
	ds_read_b128 v[170:173], v191 offset:2048
	ds_read_b128 v[174:177], v191 offset:3072
	ds_read_b128 v[196:199], v191 offset:4096
	ds_read_b128 v[200:203], v191 offset:5120
	ds_read_b128 v[204:207], v191 offset:6144
	ds_read_b128 v[208:211], v191 offset:7168
	global_load_lds_dwordx4 v184, s[60:61]
	s_mov_b32 m0, s49
	s_nop 0
	global_load_lds_dwordx4 v188, s[60:61]
	s_waitcnt vmcnt(8)
	s_waitcnt lgkmcnt(0)
	s_barrier
	s_setprio 1
	s_waitcnt lgkmcnt(0)
	v_mfma_f32_16x16x128_f8f6f4 v[124:127], v[130:137], v[162:169], v[124:127]
	v_mfma_f32_16x16x128_f8f6f4 v[120:123], v[138:145], v[162:169], v[120:123]
	v_mfma_f32_16x16x128_f8f6f4 v[108:111], v[130:137], v[170:177], v[108:111]
	v_mfma_f32_16x16x128_f8f6f4 v[104:107], v[138:145], v[170:177], v[104:107]
	v_mfma_f32_16x16x128_f8f6f4 v[178:181], v[130:137], v[196:203], v[92:95]
	v_mfma_f32_16x16x128_f8f6f4 v[216:219], v[138:145], v[196:203], v[88:91]
	v_mfma_f32_16x16x128_f8f6f4 v[220:223], v[130:137], v[204:211], v[76:79]
	v_mfma_f32_16x16x128_f8f6f4 v[224:227], v[138:145], v[204:211], v[72:75]
	s_setprio 0
	s_setprio 1
	v_mfma_f32_16x16x128_f8f6f4 v[116:119], v[146:153], v[162:169], v[116:119]
	v_mfma_f32_16x16x128_f8f6f4 v[112:115], v[154:161], v[162:169], v[112:115]
	v_mfma_f32_16x16x128_f8f6f4 v[100:103], v[146:153], v[170:177], v[100:103]
	v_mfma_f32_16x16x128_f8f6f4 v[96:99], v[154:161], v[170:177], v[96:99]
	v_mfma_f32_16x16x128_f8f6f4 v[162:165], v[146:153], v[196:203], v[84:87]
	v_mfma_f32_16x16x128_f8f6f4 v[166:169], v[154:161], v[196:203], v[80:83]
	v_mfma_f32_16x16x128_f8f6f4 v[170:173], v[146:153], v[204:211], v[68:71]
	v_mfma_f32_16x16x128_f8f6f4 v[174:177], v[154:161], v[204:211], v[64:67]
	s_setprio 0
	s_barrier
	s_mov_b32 m0, s51
	s_nop 3
	ds_read_b128 v[64:67], v191 offset:16384
	ds_read_b128 v[68:71], v191 offset:17408
	ds_read_b128 v[72:75], v191 offset:18432
	ds_read_b128 v[76:79], v191 offset:19456
	ds_read_b128 v[80:83], v191 offset:20480
	ds_read_b128 v[84:87], v191 offset:21504
	ds_read_b128 v[88:91], v191 offset:22528
	ds_read_b128 v[92:95], v191 offset:23552
	global_load_lds_dwordx4 v186, s[26:27]
	s_mov_b32 m0, s52
	s_nop 0
	global_load_lds_dwordx4 v190, s[26:27]
	s_mov_b32 m0, s53
	s_nop 0
	global_load_lds_dwordx4 v186, s[28:29]
	s_mov_b32 m0, s54
	s_nop 0
	global_load_lds_dwordx4 v190, s[28:29]
	s_mov_b32 m0, s34
	s_nop 0
	global_load_lds_dwordx4 v184, s[24:25]
	s_mov_b32 m0, s35
	s_nop 0
	global_load_lds_dwordx4 v188, s[24:25]
	s_waitcnt vmcnt(8)
	s_waitcnt lgkmcnt(0)
	s_barrier
	s_setprio 1
	s_waitcnt lgkmcnt(0)
	v_mfma_f32_16x16x128_f8f6f4 v[60:63], v[130:137], v[64:71], v[60:63]
	v_mfma_f32_16x16x128_f8f6f4 v[56:59], v[138:145], v[64:71], v[56:59]
	v_mfma_f32_16x16x128_f8f6f4 v[196:199], v[130:137], v[72:79], v[44:47]
	v_mfma_f32_16x16x128_f8f6f4 v[200:203], v[138:145], v[72:79], v[40:43]
	v_mfma_f32_16x16x128_f8f6f4 v[204:207], v[130:137], v[80:87], v[28:31]
	v_mfma_f32_16x16x128_f8f6f4 v[208:211], v[138:145], v[80:87], v[24:27]
	v_mfma_f32_16x16x128_f8f6f4 v[228:231], v[130:137], v[88:95], v[12:15]
	v_mfma_f32_16x16x128_f8f6f4 v[232:235], v[138:145], v[88:95], v[8:11]
	s_setprio 0
	s_setprio 1
	v_mfma_f32_16x16x128_f8f6f4 v[52:55], v[146:153], v[64:71], v[52:55]
	v_mfma_f32_16x16x128_f8f6f4 v[48:51], v[154:161], v[64:71], v[48:51]
	v_mfma_f32_16x16x128_f8f6f4 v[236:239], v[146:153], v[72:79], v[36:39]
	v_mfma_f32_16x16x128_f8f6f4 v[240:243], v[154:161], v[72:79], v[32:35]
	v_mfma_f32_16x16x128_f8f6f4 v[244:247], v[146:153], v[80:87], v[20:23]
	v_mfma_f32_16x16x128_f8f6f4 v[248:251], v[154:161], v[80:87], v[16:19]
	v_mfma_f32_16x16x128_f8f6f4 v[192:195], v[146:153], v[88:95], v[4:7]
	v_mfma_f32_16x16x128_f8f6f4 v[212:215], v[154:161], v[88:95], v[0:3]
	s_setprio 0
	s_barrier
	s_nop 4
	ds_read_b128 v[0:3], v128
	ds_read_b128 v[4:7], v128 offset:1024
	ds_read_b128 v[16:19], v128 offset:2048
	ds_read_b128 v[20:23], v128 offset:3072
	ds_read_b128 v[130:133], v129
	ds_read_b128 v[134:137], v129 offset:1024
	ds_read_b128 v[138:141], v129 offset:2048
	ds_read_b128 v[142:145], v129 offset:3072
	s_mov_b32 m0, s36
	ds_read_b128 v[8:11], v191 offset:32768
	ds_read_b128 v[12:15], v191 offset:33792
	ds_read_b128 v[24:27], v191 offset:34816
	ds_read_b128 v[28:31], v191 offset:35840
	ds_read_b128 v[32:35], v191 offset:36864
	ds_read_b128 v[36:39], v191 offset:37888
	ds_read_b128 v[40:43], v191 offset:38912
	ds_read_b128 v[44:47], v191 offset:39936
	global_load_lds_dwordx4 v184, s[22:23]
	s_mov_b32 m0, s37
	s_nop 0
	global_load_lds_dwordx4 v188, s[22:23]
	s_waitcnt vmcnt(8)
	s_waitcnt lgkmcnt(0)
	s_barrier
; #define PG8_MMA(ai, bj, At, Bt) do { __builtin_amdgcn_s_setprio(1); _Pragma("unroll") for (int m = 0; m < 4; ++m) _Pragma("unroll") for (int n = 0; n < 2; ++n) _Pragma("unroll") for (int k = 0; k < 2; ++k) \
;         acc[ai][bj][m][n] = __builtin_amdgcn_mfma_f32_16x16x32_bf16(Bt[n][k], At[m][k], acc[ai][bj][m][n], 0, 0, 0); __builtin_amdgcn_s_setprio(0); } while (0)
; #define PG8_MMA8(ai, bj, At, Bt) do { __builtin_amdgcn_s_setprio(1); _Pragma("unroll") for (int m = 0; m < 4; ++m) _Pragma("unroll") for (int n = 0; n < 2; ++n) \
;         acc[ai][bj][m][n] = __builtin_amdgcn_mfma_scale_f32_16x16x128_f8f6f4(PG8_CAT(Bt[n][0], Bt[n][1]), PG8_CAT(At[m][0], At[m][1]), acc[ai][bj][m][n], 0, 0, 0, 0, 0, 0); __builtin_amdgcn_s_setprio(0); } while (0)
;     __device__ __forceinline__ void operator()(const f32x4 (&acc)[2][2][4][2], const Unit& u, int wr, int wc, int fr, int fq) const {
;     ...
;             for (int m = 0; m < 4; ++m) { const size_t off = (size_t)(row0 + ai * HALF + m * 16) * ldc + col0;
; #pragma unroll
;                 for (int bj = 0; bj < 2; ++bj) bv[ai][m][bj] = __builtin_nontemporal_load((const u32x4*)(xb + off + bj * HALF)); }
;     ...
;         { const int tmid = (TSW > 0 && TSW < nt) ? TSW : nt;
;           _Pragma("unroll 1") for (int t = 0; t < tmid; t += 2) { PG8_BODY(PG8_MMA) }
;           if constexpr (TSW > 0) { _Pragma("unroll 1") for (int t = tmid; t < nt; t += 2) { PG8_BODY(PG8_MMA8) } } }
	s_setprio 1
	s_waitcnt lgkmcnt(0)
	v_mfma_f32_16x16x128_f8f6f4 v[124:127], v[0:7], v[8:15], v[124:127]
	v_mfma_f32_16x16x128_f8f6f4 v[120:123], v[16:23], v[8:15], v[120:123]
	v_mfma_f32_16x16x128_f8f6f4 v[108:111], v[0:7], v[24:31], v[108:111]
	v_mfma_f32_16x16x128_f8f6f4 v[104:107], v[16:23], v[24:31], v[104:107]
	v_mfma_f32_16x16x128_f8f6f4 v[92:95], v[0:7], v[32:39], v[178:181]
	v_mfma_f32_16x16x128_f8f6f4 v[88:91], v[16:23], v[32:39], v[216:219]
	v_mfma_f32_16x16x128_f8f6f4 v[76:79], v[0:7], v[40:47], v[220:223]
	v_mfma_f32_16x16x128_f8f6f4 v[72:75], v[16:23], v[40:47], v[224:227]
	s_setprio 0
	s_setprio 1
	v_mfma_f32_16x16x128_f8f6f4 v[116:119], v[130:137], v[8:15], v[116:119]
	v_mfma_f32_16x16x128_f8f6f4 v[112:115], v[138:145], v[8:15], v[112:115]
	v_mfma_f32_16x16x128_f8f6f4 v[100:103], v[130:137], v[24:31], v[100:103]
	v_mfma_f32_16x16x128_f8f6f4 v[96:99], v[138:145], v[24:31], v[96:99]
	v_mfma_f32_16x16x128_f8f6f4 v[84:87], v[130:137], v[32:39], v[162:165]
	v_mfma_f32_16x16x128_f8f6f4 v[80:83], v[138:145], v[32:39], v[166:169]
	v_mfma_f32_16x16x128_f8f6f4 v[68:71], v[130:137], v[40:47], v[170:173]
	v_mfma_f32_16x16x128_f8f6f4 v[64:67], v[138:145], v[40:47], v[174:177]
	s_setprio 0
	s_barrier
	s_mov_b32 m0, s30
	ds_read_b128 v[32:35], v191 offset:49152
	ds_read_b128 v[36:39], v191 offset:50176
	ds_read_b128 v[146:149], v191 offset:51200
	ds_read_b128 v[150:153], v191 offset:52224
	ds_read_b128 v[154:157], v191 offset:53248
	ds_read_b128 v[158:161], v191 offset:54272
	ds_read_b128 v[162:165], v191 offset:55296
	ds_read_b128 v[166:169], v191 offset:56320
	global_load_lds_dwordx4 v186, s[18:19]
	s_mov_b32 m0, s31
	s_nop 0
	global_load_lds_dwordx4 v190, s[18:19]
	s_mov_b32 m0, s56
	s_nop 0
	global_load_lds_dwordx4 v186, s[20:21]
	s_mov_b32 m0, s57
	s_nop 0
	global_load_lds_dwordx4 v190, s[20:21]
	s_mov_b32 m0, s39
	s_nop 0
	global_load_lds_dwordx4 v184, s[16:17]
	s_mov_b32 m0, s40
	s_nop 0
	global_load_lds_dwordx4 v188, s[16:17]
	s_waitcnt vmcnt(8)
	s_waitcnt lgkmcnt(0)
	s_barrier
	s_setprio 1
	s_waitcnt lgkmcnt(0)
	v_mfma_f32_16x16x128_f8f6f4 v[60:63], v[0:7], v[32:39], v[60:63]
	v_mfma_f32_16x16x128_f8f6f4 v[56:59], v[16:23], v[32:39], v[56:59]
	v_mfma_f32_16x16x128_f8f6f4 v[44:47], v[0:7], v[146:153], v[196:199]
	v_mfma_f32_16x16x128_f8f6f4 v[40:43], v[16:23], v[146:153], v[200:203]
	v_mfma_f32_16x16x128_f8f6f4 v[28:31], v[0:7], v[154:161], v[204:207]
	v_mfma_f32_16x16x128_f8f6f4 v[24:27], v[16:23], v[154:161], v[208:211]
	v_mfma_f32_16x16x128_f8f6f4 v[12:15], v[0:7], v[162:169], v[228:231]
	v_mfma_f32_16x16x128_f8f6f4 v[8:11], v[16:23], v[162:169], v[232:235]
	s_setprio 0
	s_setprio 1
	v_mfma_f32_16x16x128_f8f6f4 v[52:55], v[130:137], v[32:39], v[52:55]
	v_mfma_f32_16x16x128_f8f6f4 v[48:51], v[138:145], v[32:39], v[48:51]
	v_mfma_f32_16x16x128_f8f6f4 v[36:39], v[130:137], v[146:153], v[236:239]
	v_mfma_f32_16x16x128_f8f6f4 v[32:35], v[138:145], v[146:153], v[240:243]
	v_mfma_f32_16x16x128_f8f6f4 v[20:23], v[130:137], v[154:161], v[244:247]
	v_mfma_f32_16x16x128_f8f6f4 v[16:19], v[138:145], v[154:161], v[248:251]
	v_mfma_f32_16x16x128_f8f6f4 v[4:7], v[130:137], v[162:169], v[192:195]
	v_mfma_f32_16x16x128_f8f6f4 v[0:3], v[138:145], v[162:169], v[212:215]
	s_setprio 0
	s_barrier
	s_add_i32 s59, s59, 2
	s_add_u32 s55, s55, 0x100
	s_addc_u32 s58, s58, 0
	s_mov_b64 s[20:21], s[6:7]
	s_cmp_eq_u32 s59, 20
	s_cbranch_scc1 mk_p4_chk
	s_cmp_gt_u32 s59, 21
	s_cbranch_scc0 .LBB0_623
	s_branch mk_p4_exit
mk_p4_chk:
	s_cmp_lg_u64 s[4:5], 0
	s_cbranch_scc0 .LBB0_623
	v_readlane_b32 s98, v254, 20
	v_readlane_b32 s99, v254, 21
	s_lshl_b32 s100, s15, 8
	s_add_i32 s100, s100, s48
	s_lshl_b32 s100, s100, 12
	s_lshl_b32 s101, s14, 8
	s_or_b32 s101, s101, s50
	s_lshl_b32 s101, s101, 1
	s_add_u32 s100, s100, s101
	s_nop 3
	s_add_u32 s98, s98, s100
	s_addc_u32 s99, s99, 0
	s_add_u32 s100, s98, 0x100
	s_addc_u32 s101, s99, 0
	v_mbcnt_lo_u32_b32 v186, -1, 0
	v_mbcnt_hi_u32_b32 v186, -1, v186
	v_and_b32_e32 v190, 15, v186
	v_lshrrev_b32_e32 v186, 4, v186
	v_lshlrev_b32_e32 v186, 4, v186
	v_lshl_or_b32 v186, v190, 12, v186
	s_add_u32 s6, s20, 0x100
	s_addc_u32 s7, s21, 0
	s_cmp_eq_u32 s59, 20
	s_cselect_b32 s24, s10, s6
	s_cselect_b32 s25, s11, s7
	s_cselect_b32 s27, s13, s58
	s_cselect_b32 s26, s12, s55
	s_add_u32 s16, s24, 0x80
	s_addc_u32 s17, s25, 0
	s_add_u32 s18, s26, 0x80
	s_addc_u32 s19, s27, 0
	s_add_u32 s60, s20, 0x60080
	s_addc_u32 s61, s21, 0
	s_add_u32 s22, s24, 0x60000
	s_addc_u32 s23, s25, 0
	s_add_u32 s28, s26, 0x60000
	s_addc_u32 s29, s27, 0
	s_add_u32 s20, s26, 0x60080
	s_addc_u32 s21, s27, 0
	ds_read_b128 v[130:133], v187
	ds_read_b128 v[134:137], v187 offset:1024
	ds_read_b128 v[138:141], v187 offset:2048
	ds_read_b128 v[142:145], v187 offset:3072
	ds_read_b128 v[146:149], v189
	ds_read_b128 v[150:153], v189 offset:1024
	ds_read_b128 v[154:157], v189 offset:2048
	ds_read_b128 v[158:161], v189 offset:3072
	s_mov_b32 m0, s47
	ds_read_b128 v[162:165], v191
	ds_read_b128 v[166:169], v191 offset:1024
	ds_read_b128 v[170:173], v191 offset:2048
	ds_read_b128 v[174:177], v191 offset:3072
	ds_read_b128 v[196:199], v191 offset:4096
	ds_read_b128 v[200:203], v191 offset:5120
	ds_read_b128 v[204:207], v191 offset:6144
	ds_read_b128 v[208:211], v191 offset:7168
	global_load_lds_dwordx4 v184, s[60:61]
	s_mov_b32 m0, s49
	s_nop 0
	global_load_lds_dwordx4 v188, s[60:61]
	s_waitcnt vmcnt(8)
	s_waitcnt lgkmcnt(0)
	s_barrier
	s_setprio 1
	s_waitcnt lgkmcnt(0)
	v_mfma_f32_16x16x128_f8f6f4 v[124:127], v[130:137], v[162:169], v[124:127]
	v_mfma_f32_16x16x128_f8f6f4 v[120:123], v[138:145], v[162:169], v[120:123]
	v_mfma_f32_16x16x128_f8f6f4 v[108:111], v[130:137], v[170:177], v[108:111]
	v_mfma_f32_16x16x128_f8f6f4 v[104:107], v[138:145], v[170:177], v[104:107]
	v_mfma_f32_16x16x128_f8f6f4 v[178:181], v[130:137], v[196:203], v[92:95]
	v_mfma_f32_16x16x128_f8f6f4 v[216:219], v[138:145], v[196:203], v[88:91]
	v_mfma_f32_16x16x128_f8f6f4 v[220:223], v[130:137], v[204:211], v[76:79]
	v_mfma_f32_16x16x128_f8f6f4 v[224:227], v[138:145], v[204:211], v[72:75]
	s_setprio 0
	s_setprio 1
	v_mfma_f32_16x16x128_f8f6f4 v[116:119], v[146:153], v[162:169], v[116:119]
	v_mfma_f32_16x16x128_f8f6f4 v[112:115], v[154:161], v[162:169], v[112:115]
	v_mfma_f32_16x16x128_f8f6f4 v[100:103], v[146:153], v[170:177], v[100:103]
	v_mfma_f32_16x16x128_f8f6f4 v[96:99], v[154:161], v[170:177], v[96:99]
	v_mfma_f32_16x16x128_f8f6f4 v[162:165], v[146:153], v[196:203], v[84:87]
	v_mfma_f32_16x16x128_f8f6f4 v[166:169], v[154:161], v[196:203], v[80:83]
	v_mfma_f32_16x16x128_f8f6f4 v[170:173], v[146:153], v[204:211], v[68:71]
	v_mfma_f32_16x16x128_f8f6f4 v[174:177], v[154:161], v[204:211], v[64:67]
	s_setprio 0
	s_barrier
	s_mov_b32 m0, s51
	s_nop 3
	ds_read_b128 v[64:67], v191 offset:16384
	ds_read_b128 v[68:71], v191 offset:17408
	ds_read_b128 v[72:75], v191 offset:18432
	ds_read_b128 v[76:79], v191 offset:19456
	ds_read_b128 v[80:83], v191 offset:20480
	ds_read_b128 v[84:87], v191 offset:21504
	ds_read_b128 v[88:91], v191 offset:22528
	ds_read_b128 v[92:95], v191 offset:23552
	global_load_lds_dwordx4 v186, s[98:99]
	s_mov_b32 m0, s52
	s_nop 0
	global_load_lds_dwordx4 v186, s[100:101]
	s_mov_b32 m0, s53
	s_nop 0
	s_add_u32 s98, s98, 0x10000
	s_addc_u32 s99, s99, 0
	s_add_u32 s100, s100, 0x10000
	s_addc_u32 s101, s101, 0
	global_load_lds_dwordx4 v186, s[98:99]
	s_mov_b32 m0, s54
	s_nop 0
	global_load_lds_dwordx4 v186, s[100:101]
	s_mov_b32 m0, s34
	s_nop 0
	s_add_u32 s98, s98, 0x10000
	s_addc_u32 s99, s99, 0
	s_add_u32 s100, s100, 0x10000
	s_addc_u32 s101, s101, 0
	global_load_lds_dwordx4 v186, s[98:99]
	s_mov_b32 m0, s35
	s_nop 0
	global_load_lds_dwordx4 v186, s[100:101]
	s_waitcnt vmcnt(8)
	s_waitcnt lgkmcnt(0)
	s_barrier
	s_setprio 1
	s_waitcnt lgkmcnt(0)
	v_mfma_f32_16x16x128_f8f6f4 v[60:63], v[130:137], v[64:71], v[60:63]
	v_mfma_f32_16x16x128_f8f6f4 v[56:59], v[138:145], v[64:71], v[56:59]
	v_mfma_f32_16x16x128_f8f6f4 v[196:199], v[130:137], v[72:79], v[44:47]
	v_mfma_f32_16x16x128_f8f6f4 v[200:203], v[138:145], v[72:79], v[40:43]
	v_mfma_f32_16x16x128_f8f6f4 v[204:207], v[130:137], v[80:87], v[28:31]
	v_mfma_f32_16x16x128_f8f6f4 v[208:211], v[138:145], v[80:87], v[24:27]
	v_mfma_f32_16x16x128_f8f6f4 v[228:231], v[130:137], v[88:95], v[12:15]
	v_mfma_f32_16x16x128_f8f6f4 v[232:235], v[138:145], v[88:95], v[8:11]
	s_setprio 0
	s_setprio 1
	v_mfma_f32_16x16x128_f8f6f4 v[52:55], v[146:153], v[64:71], v[52:55]
	v_mfma_f32_16x16x128_f8f6f4 v[48:51], v[154:161], v[64:71], v[48:51]
	v_mfma_f32_16x16x128_f8f6f4 v[236:239], v[146:153], v[72:79], v[36:39]
	v_mfma_f32_16x16x128_f8f6f4 v[240:243], v[154:161], v[72:79], v[32:35]
	v_mfma_f32_16x16x128_f8f6f4 v[244:247], v[146:153], v[80:87], v[20:23]
	v_mfma_f32_16x16x128_f8f6f4 v[248:251], v[154:161], v[80:87], v[16:19]
	v_mfma_f32_16x16x128_f8f6f4 v[192:195], v[146:153], v[88:95], v[4:7]
	v_mfma_f32_16x16x128_f8f6f4 v[212:215], v[154:161], v[88:95], v[0:3]
	s_setprio 0
	s_barrier
	s_nop 4
	ds_read_b128 v[0:3], v128
	ds_read_b128 v[4:7], v128 offset:1024
	ds_read_b128 v[16:19], v128 offset:2048
	ds_read_b128 v[20:23], v128 offset:3072
	ds_read_b128 v[130:133], v129
	ds_read_b128 v[134:137], v129 offset:1024
	ds_read_b128 v[138:141], v129 offset:2048
	ds_read_b128 v[142:145], v129 offset:3072
	s_mov_b32 m0, s36
	ds_read_b128 v[8:11], v191 offset:32768
	ds_read_b128 v[12:15], v191 offset:33792
	ds_read_b128 v[24:27], v191 offset:34816
	ds_read_b128 v[28:31], v191 offset:35840
	ds_read_b128 v[32:35], v191 offset:36864
	ds_read_b128 v[36:39], v191 offset:37888
	ds_read_b128 v[40:43], v191 offset:38912
	ds_read_b128 v[44:47], v191 offset:39936
	s_add_u32 s98, s98, 0x10000
	s_addc_u32 s99, s99, 0
	s_add_u32 s100, s100, 0x10000
	s_addc_u32 s101, s101, 0
	global_load_lds_dwordx4 v186, s[98:99]
	s_mov_b32 m0, s37
	s_nop 0
	global_load_lds_dwordx4 v186, s[100:101]
	s_waitcnt vmcnt(8)
	s_waitcnt lgkmcnt(0)
	s_barrier
	s_setprio 1
	s_waitcnt lgkmcnt(0)
	v_mfma_f32_16x16x128_f8f6f4 v[124:127], v[0:7], v[8:15], v[124:127]
	v_mfma_f32_16x16x128_f8f6f4 v[120:123], v[16:23], v[8:15], v[120:123]
	v_mfma_f32_16x16x128_f8f6f4 v[108:111], v[0:7], v[24:31], v[108:111]
	v_mfma_f32_16x16x128_f8f6f4 v[104:107], v[16:23], v[24:31], v[104:107]
	v_mfma_f32_16x16x128_f8f6f4 v[92:95], v[0:7], v[32:39], v[178:181]
	v_mfma_f32_16x16x128_f8f6f4 v[88:91], v[16:23], v[32:39], v[216:219]
	v_mfma_f32_16x16x128_f8f6f4 v[76:79], v[0:7], v[40:47], v[220:223]
	v_mfma_f32_16x16x128_f8f6f4 v[72:75], v[16:23], v[40:47], v[224:227]
	s_setprio 0
	s_setprio 1
	v_mfma_f32_16x16x128_f8f6f4 v[116:119], v[130:137], v[8:15], v[116:119]
	v_mfma_f32_16x16x128_f8f6f4 v[112:115], v[138:145], v[8:15], v[112:115]
	v_mfma_f32_16x16x128_f8f6f4 v[100:103], v[130:137], v[24:31], v[100:103]
	v_mfma_f32_16x16x128_f8f6f4 v[96:99], v[138:145], v[24:31], v[96:99]
	v_mfma_f32_16x16x128_f8f6f4 v[84:87], v[130:137], v[32:39], v[162:165]
	v_mfma_f32_16x16x128_f8f6f4 v[80:83], v[138:145], v[32:39], v[166:169]
	v_mfma_f32_16x16x128_f8f6f4 v[68:71], v[130:137], v[40:47], v[170:173]
	v_mfma_f32_16x16x128_f8f6f4 v[64:67], v[138:145], v[40:47], v[174:177]
	s_setprio 0
	s_barrier
; __device__ __forceinline__ unsigned lane_id_fresh() { unsigned m = ~0u; asm volatile("" : "+s"(m)); return __builtin_amdgcn_mbcnt_hi(m, __builtin_amdgcn_mbcnt_lo(m, 0u)); }
;     __device__ __forceinline__ void operator()(const f32x4 (&acc)[2][2][4][2], const Unit& u, int wr, int wc, int fr, int fq) const {
;         { int l_ = (int)lane_id_fresh(); asm volatile("" : "+v"(l_)); fr = l_ & 15; fq = l_ >> 4; }
;         const int row0 = u.pm * BM + wr * 64 + fr, col0 = u.pn * BM + wc * 32 + 8 * fq;
;         u32x4 bv[2][4][2];
; #pragma unroll
;         for (int ai = 0; ai < 2; ++ai)
; #pragma unroll
;             for (int m = 0; m < 4; ++m) { const size_t off = (size_t)(row0 + ai * HALF + m * 16) * ldc + col0;
; #pragma unroll
;                 for (int bj = 0; bj < 2; ++bj) bv[ai][m][bj] = __builtin_nontemporal_load((const u32x4*)(xb + off + bj * HALF)); }
	s_mov_b32 m0, s30
	ds_read_b128 v[32:35], v191 offset:49152
	ds_read_b128 v[36:39], v191 offset:50176
	ds_read_b128 v[146:149], v191 offset:51200
	ds_read_b128 v[150:153], v191 offset:52224
	ds_read_b128 v[154:157], v191 offset:53248
	ds_read_b128 v[158:161], v191 offset:54272
	ds_read_b128 v[162:165], v191 offset:55296
	ds_read_b128 v[166:169], v191 offset:56320
	s_add_u32 s98, s98, 0x50000
	s_addc_u32 s99, s99, 0
	s_add_u32 s100, s100, 0x50000
	s_addc_u32 s101, s101, 0
	global_load_lds_dwordx4 v186, s[98:99]
	s_mov_b32 m0, s31
	s_nop 0
	global_load_lds_dwordx4 v186, s[100:101]
	s_mov_b32 m0, s56
	s_nop 0
	s_add_u32 s98, s98, 0x10000
	s_addc_u32 s99, s99, 0
	s_add_u32 s100, s100, 0x10000
	s_addc_u32 s101, s101, 0
	global_load_lds_dwordx4 v186, s[98:99]
	s_mov_b32 m0, s57
	s_nop 0
	global_load_lds_dwordx4 v186, s[100:101]
	s_mov_b32 m0, s39
	s_nop 0
	s_add_u32 s98, s98, 0x10000
	s_addc_u32 s99, s99, 0
	s_add_u32 s100, s100, 0x10000
	s_addc_u32 s101, s101, 0
	global_load_lds_dwordx4 v186, s[98:99]
	s_mov_b32 m0, s40
	s_nop 0
	global_load_lds_dwordx4 v186, s[100:101]
	s_waitcnt vmcnt(8)
	s_waitcnt lgkmcnt(0)
	s_barrier
	s_setprio 1
	s_waitcnt lgkmcnt(0)
	v_mfma_f32_16x16x128_f8f6f4 v[60:63], v[0:7], v[32:39], v[60:63]
	v_mfma_f32_16x16x128_f8f6f4 v[56:59], v[16:23], v[32:39], v[56:59]
	v_mfma_f32_16x16x128_f8f6f4 v[44:47], v[0:7], v[146:153], v[196:199]
	v_mfma_f32_16x16x128_f8f6f4 v[40:43], v[16:23], v[146:153], v[200:203]
	v_mfma_f32_16x16x128_f8f6f4 v[28:31], v[0:7], v[154:161], v[204:207]
	v_mfma_f32_16x16x128_f8f6f4 v[24:27], v[16:23], v[154:161], v[208:211]
	v_mfma_f32_16x16x128_f8f6f4 v[12:15], v[0:7], v[162:169], v[228:231]
	v_mfma_f32_16x16x128_f8f6f4 v[8:11], v[16:23], v[162:169], v[232:235]
	s_setprio 0
	s_setprio 1
	v_mfma_f32_16x16x128_f8f6f4 v[52:55], v[130:137], v[32:39], v[52:55]
	v_mfma_f32_16x16x128_f8f6f4 v[48:51], v[138:145], v[32:39], v[48:51]
	v_mfma_f32_16x16x128_f8f6f4 v[36:39], v[130:137], v[146:153], v[236:239]
	v_mfma_f32_16x16x128_f8f6f4 v[32:35], v[138:145], v[146:153], v[240:243]
	v_mfma_f32_16x16x128_f8f6f4 v[20:23], v[130:137], v[154:161], v[244:247]
	v_mfma_f32_16x16x128_f8f6f4 v[16:19], v[138:145], v[154:161], v[248:251]
	v_mfma_f32_16x16x128_f8f6f4 v[4:7], v[130:137], v[162:169], v[192:195]
	v_mfma_f32_16x16x128_f8f6f4 v[0:3], v[138:145], v[162:169], v[212:215]
	s_setprio 0
	s_barrier
	s_add_u32 s98, s98, 0x10000
	s_addc_u32 s99, s99, 0
	s_add_u32 s100, s100, 0x10000
	s_addc_u32 s101, s101, 0
	s_mov_b32 m0, s47
	s_nop 0
	global_load_lds_dwordx4 v186, s[98:99]
	s_mov_b32 m0, s49
	s_nop 0
	global_load_lds_dwordx4 v186, s[100:101]
	s_add_i32 s59, s59, 2
	s_add_u32 s55, s55, 0x100
	s_addc_u32 s58, s58, 0
	s_mov_b64 s[20:21], s[6:7]
mk_p4_exit:
	s_and_b64 vcc, exec, s[8:9]
	s_cbranch_vccz .LBB0_626
	s_barrier
.LBB0_626:
	s_mov_b32 s6, -1
	s_nop 0
	v_mbcnt_lo_u32_b32 v128, s6, 0
	v_mbcnt_hi_u32_b32 v132, s6, v128
	s_lshl_b32 s6, s15, 8
	s_add_i32 s6, s6, s48
	s_nop 0
	v_and_or_b32 v212, v132, 15, s6
	s_lshl_b32 s6, s14, 8
	v_ashrrev_i32_e32 v128, 1, v132
	s_or_b32 s6, s6, s50
	v_and_b32_e32 v128, -8, v128
	v_add_u32_e32 v196, s6, v128
	v_ashrrev_i32_e32 v197, 31, v196
	v_readlane_b32 s6, v254, 20
	v_lshlrev_b64 v[218:219], 1, v[196:197]
	v_readlane_b32 s7, v254, 21
	v_ashrrev_i32_e32 v213, 31, v212
	v_lshlrev_b64 v[220:221], 12, v[212:213]
	v_lshl_add_u64 v[128:129], s[6:7], 0, v[218:219]
	v_lshl_add_u64 v[130:131], v[128:129], 0, v[220:221]
	s_cmp_lg_u64 s[4:5], 0
	s_cbranch_scc1 mk_p4_ldsA
	global_load_dwordx4 v[192:195], v[130:131], off nt
	global_load_dwordx4 v[214:217], v[130:131], off offset:256 nt
	s_branch mk_p4_endA
mk_p4_ldsA:
	v_lshl_add_u32 v186, v132, 4, s33
	v_add_u32_e32 v190, 0x10000, v186
	s_waitcnt vmcnt(0)
	ds_read_b128 v[192:195], v190 offset:0
	ds_read_b128 v[214:217], v190 offset:8192
;     __device__ __forceinline__ const char* b(const Unit& u) const { return (const char*)Bt + (size_t)u.pn * 2 * hB() + (size_t)(u.pm >> gshift) * goff; }
;     __device__ __forceinline__ void operator()(const f32x4 (&acc)[2][2][4][2], const Unit& u, int wr, int wc, int fr, int fq) const {
;     ...
;         for (int ai = 0; ai < 2; ++ai)
; #pragma unroll
;             for (int m = 0; m < 4; ++m) { const size_t off = (size_t)(row0 + ai * HALF + m * 16) * ldc + col0;
; #pragma unroll
;                 for (int bj = 0; bj < 2; ++bj) bv[ai][m][bj] = __builtin_nontemporal_load((const u32x4*)(xb + off + bj * HALF)); }
; #pragma unroll
;         for (int ai = 0; ai < 2; ++ai)
; #pragma unroll
;             for (int m = 0; m < 4; ++m) { const int r = row0 + ai * HALF + m * 16; const size_t off = (size_t)r * ldc + col0; float s = 0.f;
; #pragma unroll
;                 for (int bj = 0; bj < 2; ++bj) { const u32x4 b = bv[ai][m][bj];
;                     f32x4 o0, o1;
;                     o0[0] = __builtin_fmaf(acc[ai][bj][m][0][0], asc, __builtin_bit_cast(float, b.x << 16)); o0[1] = __builtin_fmaf(acc[ai][bj][m][0][1], asc, __builtin_bit_cast(float, b.x & 0xffff0000u));
;                     o0[2] = __builtin_fmaf(acc[ai][bj][m][0][2], asc, __builtin_bit_cast(float, b.y << 16)); o0[3] = __builtin_fmaf(acc[ai][bj][m][0][3], asc, __builtin_bit_cast(float, b.y & 0xffff0000u));
;                     o1[0] = __builtin_fmaf(acc[ai][bj][m][1][0], asc, __builtin_bit_cast(float, b.z << 16)); o1[1] = __builtin_fmaf(acc[ai][bj][m][1][1], asc, __builtin_bit_cast(float, b.z & 0xffff0000u));
;                     o1[2] = __builtin_fmaf(acc[ai][bj][m][1][2], asc, __builtin_bit_cast(float, b.w << 16)); o1[3] = __builtin_fmaf(acc[ai][bj][m][1][3], asc, __builtin_bit_cast(float, b.w & 0xffff0000u));
;                     s += ((o0[0] * o0[0] + o0[1] * o0[1]) + (o0[2] * o0[2] + o0[3] * o0[3])) + ((o1[0] * o1[0] + o1[1] * o1[1]) + (o1[2] * o1[2] + o1[3] * o1[3]));
;                     u32x4 w; w.x = cvt_pk_bf16(o0[0], o0[1]); w.y = cvt_pk_bf16(o0[2], o0[3]); w.z = cvt_pk_bf16(o1[0], o1[1]); w.w = cvt_pk_bf16(o1[2], o1[3]);
;                     *(u32x4*)(outb + off + bj * HALF) = w; }
;                 s += __shfl_xor(s, 16); s += __shfl_xor(s, 32);
;                 if (fq == 0) atomicAdd(ssq + r, s); }
mk_p4_endA:
	v_or_b32_e32 v210, 16, v212
	v_or_b32_e32 v208, 32, v212
	v_or_b32_e32 v206, 48, v212
	v_add_u32_e32 v204, 0x80, v212
	v_add_u32_e32 v202, 0x90, v212
	v_add_u32_e32 v200, 0xa0, v212
	v_add_u32_e32 v198, 0xb0, v212
	v_ashrrev_i32_e32 v211, 31, v210
	v_ashrrev_i32_e32 v209, 31, v208
	v_ashrrev_i32_e32 v207, 31, v206
	v_ashrrev_i32_e32 v205, 31, v204
	v_ashrrev_i32_e32 v203, 31, v202
	v_ashrrev_i32_e32 v201, 31, v200
	v_ashrrev_i32_e32 v199, 31, v198
	v_cmp_gt_u32_e32 vcc, 16, v132
	v_lshlrev_b64 v[130:131], 12, v[210:211]
	v_lshlrev_b64 v[132:133], 12, v[208:209]
	v_lshlrev_b64 v[134:135], 12, v[206:207]
	v_lshlrev_b64 v[136:137], 12, v[204:205]
	v_lshlrev_b64 v[138:139], 12, v[202:203]
	v_lshlrev_b64 v[140:141], 12, v[200:201]
	v_lshlrev_b64 v[142:143], 12, v[198:199]
	v_lshl_add_u64 v[130:131], v[128:129], 0, v[130:131]
	v_lshl_add_u64 v[132:133], v[128:129], 0, v[132:133]
	v_lshl_add_u64 v[134:135], v[128:129], 0, v[134:135]
	v_lshl_add_u64 v[136:137], v[128:129], 0, v[136:137]
	v_lshl_add_u64 v[138:139], v[128:129], 0, v[138:139]
	v_lshl_add_u64 v[222:223], v[128:129], 0, v[140:141]
	v_lshl_add_u64 v[128:129], v[128:129], 0, v[142:143]
	s_cmp_lg_u64 s[4:5], 0
	s_cbranch_scc1 mk_p4_ldsB
	global_load_dwordx4 v[180:183], v[130:131], off nt
	global_load_dwordx4 v[176:179], v[130:131], off offset:256 nt
	global_load_dwordx4 v[172:175], v[132:133], off nt
	global_load_dwordx4 v[168:171], v[132:133], off offset:256 nt
	global_load_dwordx4 v[164:167], v[134:135], off nt
	global_load_dwordx4 v[160:163], v[134:135], off offset:256 nt
	global_load_dwordx4 v[156:159], v[136:137], off nt
	global_load_dwordx4 v[152:155], v[136:137], off offset:256 nt
	global_load_dwordx4 v[148:151], v[138:139], off nt
	global_load_dwordx4 v[144:147], v[138:139], off offset:256 nt
	global_load_dwordx4 v[140:143], v[222:223], off nt
	s_nop 0
	global_load_dwordx4 v[136:139], v[222:223], off offset:256 nt
	global_load_dwordx4 v[132:135], v[128:129], off nt
	s_nop 0
	global_load_dwordx4 v[128:131], v[128:129], off offset:256 nt
	s_branch mk_p4_endB
mk_p4_ldsB:
	ds_read_b128 v[180:183], v190 offset:16384
	ds_read_b128 v[176:179], v190 offset:24576
	ds_read_b128 v[172:175], v186 offset:0
	ds_read_b128 v[168:171], v186 offset:8192
	ds_read_b128 v[164:167], v186 offset:16384
	ds_read_b128 v[160:163], v186 offset:24576
	ds_read_b128 v[156:159], v190 offset:32768
	ds_read_b128 v[152:155], v190 offset:40960
	ds_read_b128 v[148:151], v190 offset:49152
	ds_read_b128 v[144:147], v190 offset:57344
	ds_read_b128 v[140:143], v186 offset:32768
	ds_read_b128 v[136:139], v186 offset:40960
	ds_read_b128 v[132:135], v186 offset:49152
	ds_read_b128 v[128:131], v186 offset:57344
mk_p4_endB:
	s_waitcnt vmcnt(0) lgkmcnt(0)
	v_lshlrev_b32_e32 v222, 16, v192
	v_and_b32_e32 v192, 0xffff0000, v192
	v_lshlrev_b32_e32 v223, 16, v193
	v_and_b32_e32 v193, 0xffff0000, v193
	v_lshlrev_b32_e32 v224, 16, v194
	v_and_b32_e32 v194, 0xffff0000, v194
	v_lshlrev_b32_e32 v225, 16, v195
	v_and_b32_e32 v195, 0xffff0000, v195
	v_lshlrev_b32_e32 v226, 16, v214
	v_and_b32_e32 v214, 0xffff0000, v214
	v_fmac_f32_e32 v192, 0x3d000000, v125
	v_fmac_f32_e32 v193, 0x3d000000, v127
	v_fmac_f32_e32 v194, 0x3d000000, v121
	v_fmac_f32_e32 v195, 0x3d000000, v123
	v_fmac_f32_e32 v222, 0x3d000000, v124
	v_fmac_f32_e32 v223, 0x3d000000, v126
	v_fmac_f32_e32 v224, 0x3d000000, v120
	v_fmac_f32_e32 v225, 0x3d000000, v122
	v_fmac_f32_e32 v226, 0x3d000000, v116
	v_mul_f32_e32 v116, v192, v192
	v_mul_f32_e32 v124, v193, v193
	v_mul_f32_e32 v125, v194, v194
	v_mul_f32_e32 v126, v195, v195
	v_fmac_f32_e32 v214, 0x3d000000, v117
	v_lshlrev_b32_e32 v117, 16, v215
	v_fmac_f32_e32 v116, v222, v222
	v_fmac_f32_e32 v124, v223, v223
	v_fmac_f32_e32 v125, v224, v224
	v_fmac_f32_e32 v126, v225, v225
	v_fmac_f32_e32 v117, 0x3d000000, v118
	v_and_b32_e32 v118, 0xffff0000, v215
	v_add_f32_e32 v116, v116, v124
	v_add_f32_e32 v124, v125, v126
	v_fmac_f32_e32 v118, 0x3d000000, v119
	v_lshlrev_b32_e32 v119, 16, v216
	v_and_b32_e32 v126, 0xffff0000, v216
	v_cvt_pk_bf16_f32 v120, v222, v192
	v_fmac_f32_e32 v119, 0x3d000000, v112
	v_fmac_f32_e32 v126, 0x3d000000, v113
	v_and_b32_e32 v192, 0xffff0000, v217
	v_mul_f32_e32 v112, v214, v214
	v_mul_f32_e32 v113, v118, v118
	v_lshlrev_b32_e32 v127, 16, v217
	v_fmac_f32_e32 v192, 0x3d000000, v115
	v_fmac_f32_e32 v112, v226, v226
	v_fmac_f32_e32 v113, v117, v117
	v_fmac_f32_e32 v127, 0x3d000000, v114
	v_add_f32_e32 v112, v112, v113
	v_mul_f32_e32 v113, v126, v126
	v_mul_f32_e32 v114, v192, v192
	v_fmac_f32_e32 v113, v119, v119
	v_fmac_f32_e32 v114, v127, v127
	v_add_f32_e32 v113, v113, v114
	v_add_f32_e32 v116, v116, v124
	v_add_f32_e32 v112, v112, v113
	v_and_b32_e32 v114, 64, v252
	v_cvt_pk_bf16_f32 v121, v223, v193
	v_add_f32_e32 v113, v116, v112
	v_xor_b32_e32 v112, 16, v252
	v_add_u32_e32 v193, 64, v114
	v_cmp_lt_i32_e64 s[6:7], v112, v193
	v_cvt_pk_bf16_f32 v122, v224, v194
	v_lshl_add_u64 v[114:115], s[74:75], 0, v[220:221]
	v_lshl_add_u64 v[124:125], v[114:115], 0, v[218:219]
	v_cndmask_b32_e64 v112, v252, v112, s[6:7]
	v_lshlrev_b32_e32 v112, 2, v112
	ds_bpermute_b32 v194, v112, v113
	v_cvt_pk_bf16_f32 v123, v225, v195
	global_store_dwordx4 v[124:125], v[120:123], off
	v_cvt_pk_bf16_f32 v116, v226, v214
	v_cvt_pk_bf16_f32 v117, v117, v118
	s_waitcnt lgkmcnt(0)
	v_add_f32_e32 v114, v113, v194
	v_xor_b32_e32 v113, 32, v252
	v_cmp_lt_i32_e64 s[6:7], v113, v193
	v_cvt_pk_bf16_f32 v118, v119, v126
	v_cvt_pk_bf16_f32 v119, v127, v192
	global_store_dwordx4 v[124:125], v[116:119], off offset:256
	s_nop 0
	v_cndmask_b32_e64 v113, v252, v113, s[6:7]
	v_lshlrev_b32_e32 v113, 2, v113
	ds_bpermute_b32 v115, v113, v114
	s_and_saveexec_b64 s[6:7], vcc
	s_cbranch_execz .LBB0_628
	v_lshl_add_u64 v[116:117], v[212:213], 2, s[66:67]
	s_waitcnt lgkmcnt(0)
	v_add_f32_e32 v114, v114, v115
	global_atomic_add_f32 v[116:117], v114, off
